# as before + P0 pool-weight prep tile loads/gain loads batched (one wait instead of 48 round trips)
# speedup vs baseline: 1.0207x; 1.0096x over previous
; DI int opaque_tid() { int t = threadIdx.x & 255; asm volatile("" : "+v"(t)); return t; }
; DI void prep_w(int vb, int nvb, const float* __restrict__ W, bf16_t* __restrict__ Wt, int K, int N, const float* __restrict__ gk, const float* __restrict__ sn, int mode, float* smf) {
;   const int ldt = K + PADK;
;   const int tid = opaque_tid();
;   const int ntn = N / 64, nt = (K / 64) * ntn;
;   for (int t0 = 0; t0 < nt; t0 += nvb) {
;     const int t = t0 + vb;
;     const bool on = t < nt;
;     const int k0 = (t / ntn) * 64, n0 = (t % ntn) * 64;
;     if (on) {
; #pragma unroll
;       for (int i = 0; i < 16; ++i) {
;         const int kk = i * 4 + (tid >> 6), nn = tid & 63;
;         float v = __builtin_nontemporal_load(W + (size_t)(k0 + kk) * N + n0 + nn);
;         if (gk) v *= gk[k0 + kk];
;         if (sn) v *= sn[n0 + nn];
;         smf[kk * 65 + nn] = v;
;       }
;     }
.LBB0_26:
	s_add_i32 s4, s95, s14
	s_cmp_lt_i32 s4, 16
	s_cselect_b64 s[58:59], -1, 0
	s_ashr_i32 s5, s4, 31
	s_lshr_b32 s5, s5, 30
	s_add_i32 s5, s4, s5
	s_lshl_b32 s6, s5, 4
	s_and_b32 s5, s5, 0x3fffffc
	s_sub_i32 s5, s4, s5
	s_and_b32 s54, s6, 0xffffffc0
	s_lshl_b32 s56, s5, 6
	s_cmp_gt_i32 s4, 15
	s_cbranch_scc1 .LBB0_92
	v_add_u32_e32 v12, s54, v17
	s_ashr_i32 s57, s56, 31
	v_ashrrev_i32_e32 v13, 31, v12
	v_lshl_add_u64 v[8:9], s[56:57], 2, v[6:7]
	v_lshlrev_b64 v[10:11], 10, v[12:13]
	v_lshl_add_u64 v[10:11], v[8:9], 0, v[10:11]
	global_load_dword v50, v[10:11], off nt
	v_cmp_ne_u32_e64 s[4:5], 1, v1
	v_lshl_add_u64 v[10:11], v[12:13], 2, s[38:39]
	v_or_b32_e32 v14, s56, v19
	v_ashrrev_i32_e32 v15, 31, v14
	v_cmp_ne_u32_e64 s[6:7], 1, v16
	v_lshl_add_u64 v[14:15], v[14:15], 2, s[52:53]
	v_add_u32_e32 v44, 4, v12
	v_ashrrev_i32_e32 v45, 31, v44
	v_lshlrev_b64 v[44:45], 10, v[44:45]
	v_lshl_add_u64 v[44:45], v[8:9], 0, v[44:45]
	global_load_dword v51, v[44:45], off nt
	v_add_u32_e32 v44, 8, v12
	v_ashrrev_i32_e32 v45, 31, v44
	v_lshlrev_b64 v[44:45], 10, v[44:45]
	v_lshl_add_u64 v[44:45], v[8:9], 0, v[44:45]
	global_load_dword v52, v[44:45], off nt
	v_add_u32_e32 v44, 12, v12
	v_ashrrev_i32_e32 v45, 31, v44
	v_lshlrev_b64 v[44:45], 10, v[44:45]
	v_lshl_add_u64 v[44:45], v[8:9], 0, v[44:45]
	global_load_dword v53, v[44:45], off nt
	v_add_u32_e32 v44, 16, v12
	v_ashrrev_i32_e32 v45, 31, v44
	v_lshlrev_b64 v[44:45], 10, v[44:45]
	v_lshl_add_u64 v[44:45], v[8:9], 0, v[44:45]
	global_load_dword v54, v[44:45], off nt
	v_add_u32_e32 v44, 20, v12
	v_ashrrev_i32_e32 v45, 31, v44
	v_lshlrev_b64 v[44:45], 10, v[44:45]
	v_lshl_add_u64 v[44:45], v[8:9], 0, v[44:45]
	global_load_dword v55, v[44:45], off nt
	v_add_u32_e32 v44, 24, v12
	v_ashrrev_i32_e32 v45, 31, v44
	v_lshlrev_b64 v[44:45], 10, v[44:45]
	v_lshl_add_u64 v[44:45], v[8:9], 0, v[44:45]
	global_load_dword v56, v[44:45], off nt
	v_add_u32_e32 v44, 28, v12
	v_ashrrev_i32_e32 v45, 31, v44
	v_lshlrev_b64 v[44:45], 10, v[44:45]
	v_lshl_add_u64 v[44:45], v[8:9], 0, v[44:45]
	global_load_dword v57, v[44:45], off nt
	v_add_u32_e32 v44, 32, v12
	v_ashrrev_i32_e32 v45, 31, v44
	v_lshlrev_b64 v[44:45], 10, v[44:45]
	v_lshl_add_u64 v[44:45], v[8:9], 0, v[44:45]
	global_load_dword v58, v[44:45], off nt
	v_add_u32_e32 v44, 36, v12
	v_ashrrev_i32_e32 v45, 31, v44
	v_lshlrev_b64 v[44:45], 10, v[44:45]
	v_lshl_add_u64 v[44:45], v[8:9], 0, v[44:45]
	global_load_dword v59, v[44:45], off nt
	v_add_u32_e32 v44, 40, v12
	v_ashrrev_i32_e32 v45, 31, v44
	v_lshlrev_b64 v[44:45], 10, v[44:45]
	v_lshl_add_u64 v[44:45], v[8:9], 0, v[44:45]
	global_load_dword v60, v[44:45], off nt
	v_add_u32_e32 v44, 44, v12
	v_ashrrev_i32_e32 v45, 31, v44
	v_lshlrev_b64 v[44:45], 10, v[44:45]
	v_lshl_add_u64 v[44:45], v[8:9], 0, v[44:45]
	global_load_dword v61, v[44:45], off nt
	v_add_u32_e32 v44, 48, v12
	v_ashrrev_i32_e32 v45, 31, v44
	v_lshlrev_b64 v[44:45], 10, v[44:45]
	v_lshl_add_u64 v[44:45], v[8:9], 0, v[44:45]
	global_load_dword v62, v[44:45], off nt
	v_add_u32_e32 v44, 52, v12
	v_ashrrev_i32_e32 v45, 31, v44
	v_lshlrev_b64 v[44:45], 10, v[44:45]
	v_lshl_add_u64 v[44:45], v[8:9], 0, v[44:45]
	global_load_dword v63, v[44:45], off nt
	v_add_u32_e32 v44, 56, v12
	v_ashrrev_i32_e32 v45, 31, v44
	v_lshlrev_b64 v[44:45], 10, v[44:45]
	v_lshl_add_u64 v[44:45], v[8:9], 0, v[44:45]
	global_load_dword v64, v[44:45], off nt
	v_add_u32_e32 v44, 60, v12
	v_ashrrev_i32_e32 v45, 31, v44
	v_lshlrev_b64 v[44:45], 10, v[44:45]
	v_lshl_add_u64 v[44:45], v[8:9], 0, v[44:45]
	global_load_dword v65, v[44:45], off nt
	s_andn2_b64 vcc, exec, s[16:17]
	s_cbranch_vccnz .Lpw26_a
	global_load_dword v66, v[10:11], off
	global_load_dword v67, v[10:11], off offset:16
	global_load_dword v68, v[10:11], off offset:32
	global_load_dword v69, v[10:11], off offset:48
	global_load_dword v70, v[10:11], off offset:64
	global_load_dword v71, v[10:11], off offset:80
	global_load_dword v72, v[10:11], off offset:96
	global_load_dword v73, v[10:11], off offset:112
	global_load_dword v74, v[10:11], off offset:128
	global_load_dword v75, v[10:11], off offset:144
	global_load_dword v76, v[10:11], off offset:160
	global_load_dword v77, v[10:11], off offset:176
	global_load_dword v78, v[10:11], off offset:192
	global_load_dword v79, v[10:11], off offset:208
	global_load_dword v80, v[10:11], off offset:224
	global_load_dword v81, v[10:11], off offset:240
.Lpw26_a:
	s_andn2_b64 vcc, exec, s[18:19]
	s_cbranch_vccnz .Lpw26_b
	global_load_dword v82, v[14:15], off
.Lpw26_b:
	s_waitcnt vmcnt(0)
	s_andn2_b64 vcc, exec, s[16:17]
	s_cbranch_vccnz .Lpw26_c
	v_mul_f32_e32 v50, v50, v66
	v_mul_f32_e32 v51, v51, v67
	v_mul_f32_e32 v52, v52, v68
	v_mul_f32_e32 v53, v53, v69
	v_mul_f32_e32 v54, v54, v70
	v_mul_f32_e32 v55, v55, v71
	v_mul_f32_e32 v56, v56, v72
	v_mul_f32_e32 v57, v57, v73
	v_mul_f32_e32 v58, v58, v74
	v_mul_f32_e32 v59, v59, v75
	v_mul_f32_e32 v60, v60, v76
	v_mul_f32_e32 v61, v61, v77
	v_mul_f32_e32 v62, v62, v78
	v_mul_f32_e32 v63, v63, v79
	v_mul_f32_e32 v64, v64, v80
	v_mul_f32_e32 v65, v65, v81
.Lpw26_c:
	s_andn2_b64 vcc, exec, s[18:19]
	s_cbranch_vccnz .Lpw26_d
	v_mul_f32_e32 v50, v50, v82
	v_mul_f32_e32 v51, v51, v82
	v_mul_f32_e32 v52, v52, v82
	v_mul_f32_e32 v53, v53, v82
	v_mul_f32_e32 v54, v54, v82
	v_mul_f32_e32 v55, v55, v82
	v_mul_f32_e32 v56, v56, v82
	v_mul_f32_e32 v57, v57, v82
	v_mul_f32_e32 v58, v58, v82
	v_mul_f32_e32 v59, v59, v82
	v_mul_f32_e32 v60, v60, v82
	v_mul_f32_e32 v61, v61, v82
	v_mul_f32_e32 v62, v62, v82
	v_mul_f32_e32 v63, v63, v82
	v_mul_f32_e32 v64, v64, v82
	v_mul_f32_e32 v65, v65, v82
.Lpw26_d:
	ds_write_b32 v22, v50
	ds_write_b32 v23, v51
	ds_write_b32 v24, v52
	ds_write_b32 v25, v53
	ds_write_b32 v26, v54
	ds_write_b32 v27, v55
	ds_write_b32 v29, v56
	ds_write_b32 v30, v57
	ds_write_b32 v31, v58
	ds_write_b32 v32, v59
	ds_write_b32 v33, v60
	ds_write_b32 v34, v61
	ds_write_b32 v35, v62
	ds_write_b32 v36, v63
	ds_write_b32 v37, v64
	ds_write_b32 v38, v65
